# v66 + de-serialized G2b epilogue in MOUT (bias and gate loads issued first)
# speedup vs baseline: 1.0082x; 1.0082x over previous
.LBB1_808:
	s_lshl_b32 s19, s18, 8
	s_add_i32 s19, s19, 0x80
	s_min_u32 s19, s19, 0x780
	s_add_u32 s40, s8, s19
	s_addc_u32 s41, s9, 0
	s_add_u32 s42, s10, s19
	s_addc_u32 s43, s11, 0
	ds_read_b128 v[142:145], v234 offset:0
	ds_read_b128 v[146:149], v234 offset:2048
	ds_read_b128 v[150:153], v234 offset:4096
	ds_read_b128 v[154:157], v234 offset:6144
	ds_read_b128 v[130:133], v232 offset:0
	ds_read_b128 v[134:137], v232 offset:2048
	ds_read_b128 v[138:141], v232 offset:4096
	ds_read_b128 v[216:219], v235 offset:0
	ds_read_b128 v[220:223], v235 offset:2048
	ds_read_b128 v[224:227], v235 offset:4096
	ds_read_b128 v[228:231], v235 offset:6144
	ds_read_b128 v[188:191], v233 offset:0
	ds_read_b128 v[192:195], v233 offset:2048
	ds_read_b128 v[196:199], v233 offset:4096
	s_waitcnt lgkmcnt(9)
	s_add_i32 m0, s16, 0x7010
	s_nop 0
	v_mfma_f32_16x16x32_bf16 v[72:75], v[142:145], v[130:133], v[72:75]
	global_load_lds_dwordx4 v238, s[40:41]
	s_add_i32 m0, s16, 0x7410
	s_add_u32 s12, s40, 0x4000
	s_addc_u32 s13, s41, 0
	v_mfma_f32_16x16x32_bf16 v[40:43], v[146:149], v[130:133], v[40:43]
	global_load_lds_dwordx4 v239, s[12:13]
	v_mfma_f32_16x16x32_bf16 v[36:39], v[150:153], v[130:133], v[36:39]
	v_mfma_f32_16x16x32_bf16 v[32:35], v[154:157], v[130:133], v[32:35]
	s_waitcnt lgkmcnt(8)
	s_add_i32 m0, s16, 0x7810
	s_add_u32 s12, s40, 0x8000
	s_addc_u32 s13, s41, 0
	v_mfma_f32_16x16x32_bf16 v[28:31], v[142:145], v[134:137], v[28:31]
	v_mfma_f32_16x16x32_bf16 v[24:27], v[146:149], v[134:137], v[24:27]
	global_load_lds_dwordx4 v238, s[12:13]
	v_mfma_f32_16x16x32_bf16 v[20:23], v[150:153], v[134:137], v[20:23]
	v_mfma_f32_16x16x32_bf16 v[16:19], v[154:157], v[134:137], v[16:19]
	s_waitcnt lgkmcnt(7)
	s_add_i32 m0, s17, 0xa010
	s_nop 0
	v_mfma_f32_16x16x32_bf16 v[12:15], v[142:145], v[138:141], v[12:15]
	v_mfma_f32_16x16x32_bf16 v[8:11], v[146:149], v[138:141], v[8:11]
	global_load_lds_dwordx4 v236, s[42:43]
	v_mfma_f32_16x16x32_bf16 v[4:7], v[150:153], v[138:141], v[4:7]
	v_mfma_f32_16x16x32_bf16 v[0:3], v[154:157], v[138:141], v[0:3]
	s_waitcnt lgkmcnt(2)
	s_add_i32 m0, s17, 0xa410
	s_add_u32 s12, s42, 0x4000
	s_addc_u32 s13, s43, 0
	v_mfma_f32_16x16x32_bf16 v[72:75], v[216:219], v[188:191], v[72:75]
	v_mfma_f32_16x16x32_bf16 v[40:43], v[220:223], v[188:191], v[40:43]
	global_load_lds_dwordx4 v237, s[12:13]
	v_mfma_f32_16x16x32_bf16 v[36:39], v[224:227], v[188:191], v[36:39]
	v_mfma_f32_16x16x32_bf16 v[32:35], v[228:231], v[188:191], v[32:35]
	s_waitcnt lgkmcnt(1)
	s_add_i32 m0, s17, 0xa810
	s_add_u32 s12, s42, 0x8000
	s_addc_u32 s13, s43, 0
	v_mfma_f32_16x16x32_bf16 v[28:31], v[216:219], v[192:195], v[28:31]
	v_mfma_f32_16x16x32_bf16 v[24:27], v[220:223], v[192:195], v[24:27]
	global_load_lds_dwordx4 v236, s[12:13]
	v_mfma_f32_16x16x32_bf16 v[20:23], v[224:227], v[192:195], v[20:23]
	v_mfma_f32_16x16x32_bf16 v[16:19], v[228:231], v[192:195], v[16:19]
	s_waitcnt lgkmcnt(0)
	s_add_i32 m0, s17, 0xac10
	s_add_u32 s12, s42, 0xc000
	s_addc_u32 s13, s43, 0
	v_mfma_f32_16x16x32_bf16 v[12:15], v[216:219], v[196:199], v[12:15]
	v_mfma_f32_16x16x32_bf16 v[8:11], v[220:223], v[196:199], v[8:11]
	global_load_lds_dwordx4 v237, s[12:13]
	v_mfma_f32_16x16x32_bf16 v[4:7], v[224:227], v[196:199], v[4:7]
	v_mfma_f32_16x16x32_bf16 v[0:3], v[228:231], v[196:199], v[0:3]
	s_waitcnt vmcnt(0)
	s_barrier
	s_lshl_b32 s19, s18, 8
	s_add_i32 s19, s19, 0x100
	s_min_u32 s19, s19, 0x780
	s_add_u32 s40, s8, s19
	s_addc_u32 s41, s9, 0
	s_add_u32 s42, s10, s19
	s_addc_u32 s43, s11, 0
	ds_read_b128 v[142:145], v234 offset:28672
	ds_read_b128 v[146:149], v234 offset:30720
	ds_read_b128 v[150:153], v234 offset:32768
	ds_read_b128 v[154:157], v234 offset:34816
	ds_read_b128 v[130:133], v232 offset:28672
	ds_read_b128 v[134:137], v232 offset:30720
	ds_read_b128 v[138:141], v232 offset:32768
	ds_read_b128 v[216:219], v235 offset:28672
	ds_read_b128 v[220:223], v235 offset:30720
	ds_read_b128 v[224:227], v235 offset:32768
	ds_read_b128 v[228:231], v235 offset:34816
	ds_read_b128 v[188:191], v233 offset:28672
	ds_read_b128 v[192:195], v233 offset:30720
	ds_read_b128 v[196:199], v233 offset:32768
	s_waitcnt lgkmcnt(9)
	s_add_i32 m0, s16, 0x10
	s_nop 0
	v_mfma_f32_16x16x32_bf16 v[72:75], v[142:145], v[130:133], v[72:75]
	global_load_lds_dwordx4 v238, s[40:41]
	s_add_i32 m0, s16, 0x410
	s_add_u32 s12, s40, 0x4000
	s_addc_u32 s13, s41, 0
	v_mfma_f32_16x16x32_bf16 v[40:43], v[146:149], v[130:133], v[40:43]
	global_load_lds_dwordx4 v239, s[12:13]
	v_mfma_f32_16x16x32_bf16 v[36:39], v[150:153], v[130:133], v[36:39]
	v_mfma_f32_16x16x32_bf16 v[32:35], v[154:157], v[130:133], v[32:35]
	s_waitcnt lgkmcnt(8)
	s_add_i32 m0, s16, 0x810
	s_add_u32 s12, s40, 0x8000
	s_addc_u32 s13, s41, 0
	v_mfma_f32_16x16x32_bf16 v[28:31], v[142:145], v[134:137], v[28:31]
	v_mfma_f32_16x16x32_bf16 v[24:27], v[146:149], v[134:137], v[24:27]
	global_load_lds_dwordx4 v238, s[12:13]
	v_mfma_f32_16x16x32_bf16 v[20:23], v[150:153], v[134:137], v[20:23]
	v_mfma_f32_16x16x32_bf16 v[16:19], v[154:157], v[134:137], v[16:19]
	s_waitcnt lgkmcnt(7)
	s_add_i32 m0, s17, 0x3010
	s_nop 0
	v_mfma_f32_16x16x32_bf16 v[12:15], v[142:145], v[138:141], v[12:15]
	v_mfma_f32_16x16x32_bf16 v[8:11], v[146:149], v[138:141], v[8:11]
	global_load_lds_dwordx4 v236, s[42:43]
	v_mfma_f32_16x16x32_bf16 v[4:7], v[150:153], v[138:141], v[4:7]
	v_mfma_f32_16x16x32_bf16 v[0:3], v[154:157], v[138:141], v[0:3]
	s_waitcnt lgkmcnt(2)
	s_add_i32 m0, s17, 0x3410
	s_add_u32 s12, s42, 0x4000
	s_addc_u32 s13, s43, 0
	v_mfma_f32_16x16x32_bf16 v[72:75], v[216:219], v[188:191], v[72:75]
	v_mfma_f32_16x16x32_bf16 v[40:43], v[220:223], v[188:191], v[40:43]
	global_load_lds_dwordx4 v237, s[12:13]
	v_mfma_f32_16x16x32_bf16 v[36:39], v[224:227], v[188:191], v[36:39]
	v_mfma_f32_16x16x32_bf16 v[32:35], v[228:231], v[188:191], v[32:35]
	s_waitcnt lgkmcnt(1)
	s_add_i32 m0, s17, 0x3810
	s_add_u32 s12, s42, 0x8000
	s_addc_u32 s13, s43, 0
	v_mfma_f32_16x16x32_bf16 v[28:31], v[216:219], v[192:195], v[28:31]
	v_mfma_f32_16x16x32_bf16 v[24:27], v[220:223], v[192:195], v[24:27]
	global_load_lds_dwordx4 v236, s[12:13]
	v_mfma_f32_16x16x32_bf16 v[20:23], v[224:227], v[192:195], v[20:23]
	v_mfma_f32_16x16x32_bf16 v[16:19], v[228:231], v[192:195], v[16:19]
	s_waitcnt lgkmcnt(0)
	s_add_i32 m0, s17, 0x3c10
	s_add_u32 s12, s42, 0xc000
	s_addc_u32 s13, s43, 0
	v_mfma_f32_16x16x32_bf16 v[12:15], v[216:219], v[196:199], v[12:15]
	v_mfma_f32_16x16x32_bf16 v[8:11], v[220:223], v[196:199], v[8:11]
	global_load_lds_dwordx4 v237, s[12:13]
	v_mfma_f32_16x16x32_bf16 v[4:7], v[224:227], v[196:199], v[4:7]
	v_mfma_f32_16x16x32_bf16 v[0:3], v[228:231], v[196:199], v[0:3]
	s_waitcnt vmcnt(0)
	s_barrier
	s_add_i32 s18, s18, 1
	s_cmp_eq_u32 s18, 8
	s_cbranch_scc0 .LBB1_808
	s_setprio 0
	s_waitcnt vmcnt(0)
	v_and_b32_e32 v154, 15, v168
	v_lshrrev_b32_e32 v155, 4, v168
	v_lshrrev_b32_e32 v156, 7, v162
	v_bfe_u32 v157, v162, 6, 1
	v_mul_u32_u24_e32 v156, 48, v156
	v_add3_u32 v156, v156, v154, s5
	v_lshlrev_b32_e32 v157, 6, v157
	v_lshl_add_u32 v157, v155, 2, v157
	v_add_u32_e32 v157, s4, v157
	v_lshlrev_b32_e32 v53, 2, v157
	v_lshlrev_b32_e32 v158, 1, v157
	v_lshl_add_u32 v44, v156, 14, v158
	v_lshl_add_u32 v47, v156, 12, v53
	v_add_u32_e32 v156, 16, v156
	v_lshlrev_b32_e32 v158, 1, v157
	v_lshl_add_u32 v45, v156, 14, v158
	v_lshl_add_u32 v48, v156, 12, v53
	v_add_u32_e32 v156, 16, v156
	v_lshlrev_b32_e32 v158, 1, v157
	v_lshl_add_u32 v46, v156, 14, v158
	v_lshl_add_u32 v49, v156, 12, v53
	s_add_u32 s10, s76, 0x3800
	s_addc_u32 s11, s77, 0
	global_load_dwordx4 v[54:57], v53, s[14:15] offset:0
	global_load_dwordx4 v[58:61], v53, s[14:15] offset:64
	global_load_dwordx4 v[62:65], v53, s[14:15] offset:128
	global_load_dwordx4 v[66:69], v53, s[14:15] offset:192
	global_load_dwordx2 v[188:189], v44, s[10:11] offset:0
	global_load_dwordx2 v[190:191], v44, s[10:11] offset:32
	global_load_dwordx2 v[192:193], v44, s[10:11] offset:64
	global_load_dwordx2 v[194:195], v44, s[10:11] offset:96
	global_load_dwordx2 v[196:197], v45, s[10:11] offset:0
	global_load_dwordx2 v[198:199], v45, s[10:11] offset:32
	global_load_dwordx2 v[200:201], v45, s[10:11] offset:64
	global_load_dwordx2 v[202:203], v45, s[10:11] offset:96
	global_load_dwordx2 v[204:205], v46, s[10:11] offset:0
	global_load_dwordx2 v[206:207], v46, s[10:11] offset:32
	global_load_dwordx2 v[208:209], v46, s[10:11] offset:64
	global_load_dwordx2 v[210:211], v46, s[10:11] offset:96
	s_waitcnt vmcnt(11)
	v_lshlrev_b32_e32 v150, 16, v188
	v_and_b32_e32 v151, 0xffff0000, v188
	v_lshlrev_b32_e32 v152, 16, v189
	v_and_b32_e32 v153, 0xffff0000, v189
	v_pk_add_f32 v[150:151], v[54:55], v[150:151]
	v_pk_add_f32 v[152:153], v[56:57], v[152:153]
	s_nop 0
	v_mul_f32_e32 v150, 0xbfb8aa3b, v150
	v_mul_f32_e32 v151, 0xbfb8aa3b, v151
	v_mul_f32_e32 v152, 0xbfb8aa3b, v152
	v_mul_f32_e32 v153, 0xbfb8aa3b, v153
	v_exp_f32_e32 v150, v150
	v_exp_f32_e32 v151, v151
	v_exp_f32_e32 v152, v152
	v_exp_f32_e32 v153, v153
	v_add_f32_e32 v150, 1.0, v150
	v_add_f32_e32 v151, 1.0, v151
	v_add_f32_e32 v152, 1.0, v152
	v_add_f32_e32 v153, 1.0, v153
	v_rcp_f32_e32 v150, v150
	v_rcp_f32_e32 v151, v151
	v_rcp_f32_e32 v152, v152
	v_rcp_f32_e32 v153, v153
	v_pk_mul_f32 v[72:73], v[72:73], v[150:151]
	v_pk_mul_f32 v[74:75], v[74:75], v[152:153]
	s_nop 0
	global_store_dwordx4 v47, v[72:75], s[72:73] offset:0
	s_waitcnt vmcnt(10)
	v_lshlrev_b32_e32 v150, 16, v190
	v_and_b32_e32 v151, 0xffff0000, v190
	v_lshlrev_b32_e32 v152, 16, v191
	v_and_b32_e32 v153, 0xffff0000, v191
	v_pk_add_f32 v[150:151], v[58:59], v[150:151]
	v_pk_add_f32 v[152:153], v[60:61], v[152:153]
	s_nop 0
	v_mul_f32_e32 v150, 0xbfb8aa3b, v150
	v_mul_f32_e32 v151, 0xbfb8aa3b, v151
	v_mul_f32_e32 v152, 0xbfb8aa3b, v152
	v_mul_f32_e32 v153, 0xbfb8aa3b, v153
	v_exp_f32_e32 v150, v150
	v_exp_f32_e32 v151, v151
	v_exp_f32_e32 v152, v152
	v_exp_f32_e32 v153, v153
	v_add_f32_e32 v150, 1.0, v150
	v_add_f32_e32 v151, 1.0, v151
	v_add_f32_e32 v152, 1.0, v152
	v_add_f32_e32 v153, 1.0, v153
	v_rcp_f32_e32 v150, v150
	v_rcp_f32_e32 v151, v151
	v_rcp_f32_e32 v152, v152
	v_rcp_f32_e32 v153, v153
	v_pk_mul_f32 v[40:41], v[40:41], v[150:151]
	v_pk_mul_f32 v[42:43], v[42:43], v[152:153]
	s_nop 0
	global_store_dwordx4 v47, v[40:43], s[72:73] offset:64
	s_waitcnt vmcnt(9)
	v_lshlrev_b32_e32 v150, 16, v192
	v_and_b32_e32 v151, 0xffff0000, v192
	v_lshlrev_b32_e32 v152, 16, v193
	v_and_b32_e32 v153, 0xffff0000, v193
	v_pk_add_f32 v[150:151], v[62:63], v[150:151]
	v_pk_add_f32 v[152:153], v[64:65], v[152:153]
	s_nop 0
	v_mul_f32_e32 v150, 0xbfb8aa3b, v150
	v_mul_f32_e32 v151, 0xbfb8aa3b, v151
	v_mul_f32_e32 v152, 0xbfb8aa3b, v152
	v_mul_f32_e32 v153, 0xbfb8aa3b, v153
	v_exp_f32_e32 v150, v150
	v_exp_f32_e32 v151, v151
	v_exp_f32_e32 v152, v152
	v_exp_f32_e32 v153, v153
	v_add_f32_e32 v150, 1.0, v150
	v_add_f32_e32 v151, 1.0, v151
	v_add_f32_e32 v152, 1.0, v152
	v_add_f32_e32 v153, 1.0, v153
	v_rcp_f32_e32 v150, v150
	v_rcp_f32_e32 v151, v151
	v_rcp_f32_e32 v152, v152
	v_rcp_f32_e32 v153, v153
	v_pk_mul_f32 v[36:37], v[36:37], v[150:151]
	v_pk_mul_f32 v[38:39], v[38:39], v[152:153]
	s_nop 0
	global_store_dwordx4 v47, v[36:39], s[72:73] offset:128
	s_waitcnt vmcnt(8)
	v_lshlrev_b32_e32 v150, 16, v194
	v_and_b32_e32 v151, 0xffff0000, v194
	v_lshlrev_b32_e32 v152, 16, v195
	v_and_b32_e32 v153, 0xffff0000, v195
	v_pk_add_f32 v[150:151], v[66:67], v[150:151]
	v_pk_add_f32 v[152:153], v[68:69], v[152:153]
	s_nop 0
	v_mul_f32_e32 v150, 0xbfb8aa3b, v150
	v_mul_f32_e32 v151, 0xbfb8aa3b, v151
	v_mul_f32_e32 v152, 0xbfb8aa3b, v152
	v_mul_f32_e32 v153, 0xbfb8aa3b, v153
	v_exp_f32_e32 v150, v150
	v_exp_f32_e32 v151, v151
	v_exp_f32_e32 v152, v152
	v_exp_f32_e32 v153, v153
	v_add_f32_e32 v150, 1.0, v150
	v_add_f32_e32 v151, 1.0, v151
	v_add_f32_e32 v152, 1.0, v152
	v_add_f32_e32 v153, 1.0, v153
	v_rcp_f32_e32 v150, v150
	v_rcp_f32_e32 v151, v151
	v_rcp_f32_e32 v152, v152
	v_rcp_f32_e32 v153, v153
	v_pk_mul_f32 v[32:33], v[32:33], v[150:151]
	v_pk_mul_f32 v[34:35], v[34:35], v[152:153]
	s_nop 0
	global_store_dwordx4 v47, v[32:35], s[72:73] offset:192
	s_waitcnt vmcnt(7)
	v_lshlrev_b32_e32 v150, 16, v196
	v_and_b32_e32 v151, 0xffff0000, v196
	v_lshlrev_b32_e32 v152, 16, v197
	v_and_b32_e32 v153, 0xffff0000, v197
	v_pk_add_f32 v[150:151], v[54:55], v[150:151]
	v_pk_add_f32 v[152:153], v[56:57], v[152:153]
	s_nop 0
	v_mul_f32_e32 v150, 0xbfb8aa3b, v150
	v_mul_f32_e32 v151, 0xbfb8aa3b, v151
	v_mul_f32_e32 v152, 0xbfb8aa3b, v152
	v_mul_f32_e32 v153, 0xbfb8aa3b, v153
	v_exp_f32_e32 v150, v150
	v_exp_f32_e32 v151, v151
	v_exp_f32_e32 v152, v152
	v_exp_f32_e32 v153, v153
	v_add_f32_e32 v150, 1.0, v150
	v_add_f32_e32 v151, 1.0, v151
	v_add_f32_e32 v152, 1.0, v152
	v_add_f32_e32 v153, 1.0, v153
	v_rcp_f32_e32 v150, v150
	v_rcp_f32_e32 v151, v151
	v_rcp_f32_e32 v152, v152
	v_rcp_f32_e32 v153, v153
	v_pk_mul_f32 v[28:29], v[28:29], v[150:151]
	v_pk_mul_f32 v[30:31], v[30:31], v[152:153]
	s_nop 0
	global_store_dwordx4 v48, v[28:31], s[72:73] offset:0
	s_waitcnt vmcnt(6)
	v_lshlrev_b32_e32 v150, 16, v198
	v_and_b32_e32 v151, 0xffff0000, v198
	v_lshlrev_b32_e32 v152, 16, v199
	v_and_b32_e32 v153, 0xffff0000, v199
	v_pk_add_f32 v[150:151], v[58:59], v[150:151]
	v_pk_add_f32 v[152:153], v[60:61], v[152:153]
	s_nop 0
	v_mul_f32_e32 v150, 0xbfb8aa3b, v150
	v_mul_f32_e32 v151, 0xbfb8aa3b, v151
	v_mul_f32_e32 v152, 0xbfb8aa3b, v152
	v_mul_f32_e32 v153, 0xbfb8aa3b, v153
	v_exp_f32_e32 v150, v150
	v_exp_f32_e32 v151, v151
	v_exp_f32_e32 v152, v152
	v_exp_f32_e32 v153, v153
	v_add_f32_e32 v150, 1.0, v150
	v_add_f32_e32 v151, 1.0, v151
	v_add_f32_e32 v152, 1.0, v152
	v_add_f32_e32 v153, 1.0, v153
	v_rcp_f32_e32 v150, v150
	v_rcp_f32_e32 v151, v151
	v_rcp_f32_e32 v152, v152
	v_rcp_f32_e32 v153, v153
	v_pk_mul_f32 v[24:25], v[24:25], v[150:151]
	v_pk_mul_f32 v[26:27], v[26:27], v[152:153]
	s_nop 0
	global_store_dwordx4 v48, v[24:27], s[72:73] offset:64
	s_waitcnt vmcnt(5)
	v_lshlrev_b32_e32 v150, 16, v200
	v_and_b32_e32 v151, 0xffff0000, v200
	v_lshlrev_b32_e32 v152, 16, v201
	v_and_b32_e32 v153, 0xffff0000, v201
	v_pk_add_f32 v[150:151], v[62:63], v[150:151]
	v_pk_add_f32 v[152:153], v[64:65], v[152:153]
	s_nop 0
	v_mul_f32_e32 v150, 0xbfb8aa3b, v150
	v_mul_f32_e32 v151, 0xbfb8aa3b, v151
	v_mul_f32_e32 v152, 0xbfb8aa3b, v152
	v_mul_f32_e32 v153, 0xbfb8aa3b, v153
	v_exp_f32_e32 v150, v150
	v_exp_f32_e32 v151, v151
	v_exp_f32_e32 v152, v152
	v_exp_f32_e32 v153, v153
	v_add_f32_e32 v150, 1.0, v150
	v_add_f32_e32 v151, 1.0, v151
	v_add_f32_e32 v152, 1.0, v152
	v_add_f32_e32 v153, 1.0, v153
	v_rcp_f32_e32 v150, v150
	v_rcp_f32_e32 v151, v151
	v_rcp_f32_e32 v152, v152
	v_rcp_f32_e32 v153, v153
	v_pk_mul_f32 v[20:21], v[20:21], v[150:151]
	v_pk_mul_f32 v[22:23], v[22:23], v[152:153]
	s_nop 0
	global_store_dwordx4 v48, v[20:23], s[72:73] offset:128
	s_waitcnt vmcnt(4)
	v_lshlrev_b32_e32 v150, 16, v202
	v_and_b32_e32 v151, 0xffff0000, v202
	v_lshlrev_b32_e32 v152, 16, v203
	v_and_b32_e32 v153, 0xffff0000, v203
	v_pk_add_f32 v[150:151], v[66:67], v[150:151]
	v_pk_add_f32 v[152:153], v[68:69], v[152:153]
	s_nop 0
	v_mul_f32_e32 v150, 0xbfb8aa3b, v150
	v_mul_f32_e32 v151, 0xbfb8aa3b, v151
	v_mul_f32_e32 v152, 0xbfb8aa3b, v152
	v_mul_f32_e32 v153, 0xbfb8aa3b, v153
	v_exp_f32_e32 v150, v150
	v_exp_f32_e32 v151, v151
	v_exp_f32_e32 v152, v152
	v_exp_f32_e32 v153, v153
	v_add_f32_e32 v150, 1.0, v150
	v_add_f32_e32 v151, 1.0, v151
	v_add_f32_e32 v152, 1.0, v152
	v_add_f32_e32 v153, 1.0, v153
	v_rcp_f32_e32 v150, v150
	v_rcp_f32_e32 v151, v151
	v_rcp_f32_e32 v152, v152
	v_rcp_f32_e32 v153, v153
	v_pk_mul_f32 v[16:17], v[16:17], v[150:151]
	v_pk_mul_f32 v[18:19], v[18:19], v[152:153]
	s_nop 0
	global_store_dwordx4 v48, v[16:19], s[72:73] offset:192
	s_waitcnt vmcnt(3)
	v_lshlrev_b32_e32 v150, 16, v204
	v_and_b32_e32 v151, 0xffff0000, v204
	v_lshlrev_b32_e32 v152, 16, v205
	v_and_b32_e32 v153, 0xffff0000, v205
	v_pk_add_f32 v[150:151], v[54:55], v[150:151]
	v_pk_add_f32 v[152:153], v[56:57], v[152:153]
	s_nop 0
	v_mul_f32_e32 v150, 0xbfb8aa3b, v150
	v_mul_f32_e32 v151, 0xbfb8aa3b, v151
	v_mul_f32_e32 v152, 0xbfb8aa3b, v152
	v_mul_f32_e32 v153, 0xbfb8aa3b, v153
	v_exp_f32_e32 v150, v150
	v_exp_f32_e32 v151, v151
	v_exp_f32_e32 v152, v152
	v_exp_f32_e32 v153, v153
	v_add_f32_e32 v150, 1.0, v150
	v_add_f32_e32 v151, 1.0, v151
	v_add_f32_e32 v152, 1.0, v152
	v_add_f32_e32 v153, 1.0, v153
	v_rcp_f32_e32 v150, v150
	v_rcp_f32_e32 v151, v151
	v_rcp_f32_e32 v152, v152
	v_rcp_f32_e32 v153, v153
	v_pk_mul_f32 v[12:13], v[12:13], v[150:151]
	v_pk_mul_f32 v[14:15], v[14:15], v[152:153]
	s_nop 0
	global_store_dwordx4 v49, v[12:15], s[72:73] offset:0
	s_waitcnt vmcnt(2)
	v_lshlrev_b32_e32 v150, 16, v206
	v_and_b32_e32 v151, 0xffff0000, v206
	v_lshlrev_b32_e32 v152, 16, v207
	v_and_b32_e32 v153, 0xffff0000, v207
	v_pk_add_f32 v[150:151], v[58:59], v[150:151]
	v_pk_add_f32 v[152:153], v[60:61], v[152:153]
	s_nop 0
	v_mul_f32_e32 v150, 0xbfb8aa3b, v150
	v_mul_f32_e32 v151, 0xbfb8aa3b, v151
	v_mul_f32_e32 v152, 0xbfb8aa3b, v152
	v_mul_f32_e32 v153, 0xbfb8aa3b, v153
	v_exp_f32_e32 v150, v150
	v_exp_f32_e32 v151, v151
	v_exp_f32_e32 v152, v152
	v_exp_f32_e32 v153, v153
	v_add_f32_e32 v150, 1.0, v150
	v_add_f32_e32 v151, 1.0, v151
	v_add_f32_e32 v152, 1.0, v152
	v_add_f32_e32 v153, 1.0, v153
	v_rcp_f32_e32 v150, v150
	v_rcp_f32_e32 v151, v151
	v_rcp_f32_e32 v152, v152
	v_rcp_f32_e32 v153, v153
	v_pk_mul_f32 v[8:9], v[8:9], v[150:151]
	v_pk_mul_f32 v[10:11], v[10:11], v[152:153]
	s_nop 0
	global_store_dwordx4 v49, v[8:11], s[72:73] offset:64
	s_waitcnt vmcnt(1)
	v_lshlrev_b32_e32 v150, 16, v208
	v_and_b32_e32 v151, 0xffff0000, v208
	v_lshlrev_b32_e32 v152, 16, v209
	v_and_b32_e32 v153, 0xffff0000, v209
	v_pk_add_f32 v[150:151], v[62:63], v[150:151]
	v_pk_add_f32 v[152:153], v[64:65], v[152:153]
	s_nop 0
	v_mul_f32_e32 v150, 0xbfb8aa3b, v150
	v_mul_f32_e32 v151, 0xbfb8aa3b, v151
	v_mul_f32_e32 v152, 0xbfb8aa3b, v152
	v_mul_f32_e32 v153, 0xbfb8aa3b, v153
	v_exp_f32_e32 v150, v150
	v_exp_f32_e32 v151, v151
	v_exp_f32_e32 v152, v152
	v_exp_f32_e32 v153, v153
	v_add_f32_e32 v150, 1.0, v150
	v_add_f32_e32 v151, 1.0, v151
	v_add_f32_e32 v152, 1.0, v152
	v_add_f32_e32 v153, 1.0, v153
	v_rcp_f32_e32 v150, v150
	v_rcp_f32_e32 v151, v151
	v_rcp_f32_e32 v152, v152
	v_rcp_f32_e32 v153, v153
	v_pk_mul_f32 v[4:5], v[4:5], v[150:151]
	v_pk_mul_f32 v[6:7], v[6:7], v[152:153]
	s_nop 0
	global_store_dwordx4 v49, v[4:7], s[72:73] offset:128
	s_waitcnt vmcnt(0)
	v_lshlrev_b32_e32 v150, 16, v210
	v_and_b32_e32 v151, 0xffff0000, v210
	v_lshlrev_b32_e32 v152, 16, v211
	v_and_b32_e32 v153, 0xffff0000, v211
	v_pk_add_f32 v[150:151], v[66:67], v[150:151]
	v_pk_add_f32 v[152:153], v[68:69], v[152:153]
	s_nop 0
	v_mul_f32_e32 v150, 0xbfb8aa3b, v150
	v_mul_f32_e32 v151, 0xbfb8aa3b, v151
	v_mul_f32_e32 v152, 0xbfb8aa3b, v152
	v_mul_f32_e32 v153, 0xbfb8aa3b, v153
	v_exp_f32_e32 v150, v150
	v_exp_f32_e32 v151, v151
	v_exp_f32_e32 v152, v152
	v_exp_f32_e32 v153, v153
	v_add_f32_e32 v150, 1.0, v150
	v_add_f32_e32 v151, 1.0, v151
	v_add_f32_e32 v152, 1.0, v152
	v_add_f32_e32 v153, 1.0, v153
	v_rcp_f32_e32 v150, v150
	v_rcp_f32_e32 v151, v151
	v_rcp_f32_e32 v152, v152
	v_rcp_f32_e32 v153, v153
	v_pk_mul_f32 v[0:1], v[0:1], v[150:151]
	v_pk_mul_f32 v[2:3], v[2:3], v[152:153]
	s_nop 0
	global_store_dwordx4 v49, v[0:3], s[72:73] offset:192
	v_readlane_b32 s4, v242, 63
	s_nop 3
	s_add_i32 s2, s2, s4
	s_cmpk_gt_i32 s2, 0x57f
	s_cbranch_scc0 .LBB1_807
